# o16 + grid barrier release in one hop: every workgroup polls the cross-XCD generation word, per-XCD release atomic dropped
# speedup vs baseline: 1.0077x; 1.0077x over previous
.LBB0_152:
	s_or_b64 exec, exec, s[6:7]
	v_cvt_f32_u32_e32 v5, v3
	s_waitcnt vmcnt(0)
	v_readfirstlane_b32 s4, v4
	v_sub_u32_e32 v4, 0, v3
	v_rcp_iflag_f32_e32 v5, v5
	v_add_u32_e32 v6, s4, v2
	v_mul_f32_e32 v5, 0x4f7ffffe, v5
	v_cvt_u32_f32_e32 v5, v5
	v_mul_lo_u32 v2, v4, v5
	v_mul_hi_u32 v2, v5, v2
	v_add_u32_e32 v2, v5, v2
	v_mul_hi_u32 v2, v6, v2
	v_mul_lo_u32 v4, v2, v3
	v_sub_u32_e32 v4, v6, v4
	v_add_u32_e32 v5, 1, v2
	v_cmp_ge_u32_e32 vcc, v4, v3
	s_nop 1
	v_cndmask_b32_e32 v2, v2, v5, vcc
	v_sub_u32_e32 v5, v4, v3
	v_cndmask_b32_e32 v4, v4, v5, vcc
	v_add_u32_e32 v5, 1, v2
	v_cmp_ge_u32_e32 vcc, v4, v3
	v_add_u32_e32 v4, 1, v6
	s_nop 0
	v_cndmask_b32_e32 v2, v2, v5, vcc
	v_mul_lo_u32 v5, v3, v2
	v_add_u32_e32 v3, v5, v3
	v_cmp_ne_u32_e32 vcc, v4, v3
	s_and_saveexec_b64 s[4:5], vcc
	s_xor_b64 s[4:5], exec, s[4:5]
	s_cbranch_execz .LBB0_166
	s_waitcnt lgkmcnt(0)
	v_mov_b32_e32 v1, 0x3500
	global_load_dword v1, v1, s[86:87] sc1
	s_add_u32 s8, s86, 0x3500
	s_addc_u32 s9, s87, 0
	s_waitcnt vmcnt(0)
	v_cmp_eq_u32_e32 vcc, v1, v2
	s_and_saveexec_b64 s[6:7], vcc
	s_cbranch_execz .LBB0_165
	s_mov_b32 s26, 1
	s_mov_b64 s[10:11], 0
	v_mov_b32_e32 v1, 0
	s_branch .LBB0_156

.LBB0_183:
	s_or_b64 exec, exec, s[4:5]
	s_mov_b64 s[4:5], exec
	v_mbcnt_lo_u32_b32 v1, s4, 0
	v_mbcnt_hi_u32_b32 v1, s5, v1
	v_cmp_eq_u32_e32 vcc, 0, v1
	s_waitcnt vmcnt(0)
	buffer_inv sc1
	s_and_saveexec_b64 s[6:7], vcc
	s_cbranch_execz .LBB0_185
	s_bcnt1_i32_b64 s4, s[4:5]
	v_mov_b32_e32 v1, 0x2000
	v_mov_b32_e32 v2, s4
.LBB0_185:
	s_or_b64 exec, exec, s[6:7]
	s_waitcnt vmcnt(0)

.LBB0_228:
	s_or_b64 exec, exec, s[6:7]
	v_cvt_f32_u32_e32 v5, v3
	s_waitcnt vmcnt(0)
	v_readfirstlane_b32 s4, v4
	v_sub_u32_e32 v4, 0, v3
	v_rcp_iflag_f32_e32 v5, v5
	v_add_u32_e32 v6, s4, v2
	v_mul_f32_e32 v5, 0x4f7ffffe, v5
	v_cvt_u32_f32_e32 v5, v5
	v_mul_lo_u32 v2, v4, v5
	v_mul_hi_u32 v2, v5, v2
	v_add_u32_e32 v2, v5, v2
	v_mul_hi_u32 v2, v6, v2
	v_mul_lo_u32 v4, v2, v3
	v_sub_u32_e32 v4, v6, v4
	v_add_u32_e32 v5, 1, v2
	v_cmp_ge_u32_e32 vcc, v4, v3
	s_nop 1
	v_cndmask_b32_e32 v2, v2, v5, vcc
	v_sub_u32_e32 v5, v4, v3
	v_cndmask_b32_e32 v4, v4, v5, vcc
	v_add_u32_e32 v5, 1, v2
	v_cmp_ge_u32_e32 vcc, v4, v3
	v_add_u32_e32 v4, 1, v6
	s_nop 0
	v_cndmask_b32_e32 v2, v2, v5, vcc
	v_mul_lo_u32 v5, v3, v2
	v_add_u32_e32 v3, v5, v3
	v_cmp_ne_u32_e32 vcc, v4, v3
	s_and_saveexec_b64 s[4:5], vcc
	s_xor_b64 s[4:5], exec, s[4:5]
	s_cbranch_execz .LBB0_242
	s_waitcnt lgkmcnt(0)
	v_mov_b32_e32 v1, 0x3500
	global_load_dword v1, v1, s[86:87] sc1
	s_add_u32 s8, s86, 0x3500
	s_addc_u32 s9, s87, 0
	s_waitcnt vmcnt(0)
	v_cmp_eq_u32_e32 vcc, v1, v2
	s_and_saveexec_b64 s[6:7], vcc
	s_cbranch_execz .LBB0_241
	s_mov_b32 s24, 1
	s_mov_b64 s[10:11], 0
	v_mov_b32_e32 v1, 0
	s_branch .LBB0_232

.LBB0_259:
	s_or_b64 exec, exec, s[4:5]
	s_mov_b64 s[4:5], exec
	v_mbcnt_lo_u32_b32 v1, s4, 0
	v_mbcnt_hi_u32_b32 v1, s5, v1
	v_cmp_eq_u32_e32 vcc, 0, v1
	s_waitcnt vmcnt(0)
	buffer_inv sc1
	s_and_saveexec_b64 s[6:7], vcc
	s_cbranch_execz .LBB0_261
	s_bcnt1_i32_b64 s4, s[4:5]
	v_mov_b32_e32 v1, 0x2000
	v_mov_b32_e32 v2, s4
.LBB0_261:
	s_or_b64 exec, exec, s[6:7]
	s_waitcnt vmcnt(0)

.LBB0_334:
	s_or_b64 exec, exec, s[6:7]
	v_cvt_f32_u32_e32 v5, v3
	s_waitcnt vmcnt(0)
	v_readfirstlane_b32 s4, v4
	v_sub_u32_e32 v4, 0, v3
	v_rcp_iflag_f32_e32 v5, v5
	v_add_u32_e32 v6, s4, v2
	v_mul_f32_e32 v5, 0x4f7ffffe, v5
	v_cvt_u32_f32_e32 v5, v5
	v_mul_lo_u32 v2, v4, v5
	v_mul_hi_u32 v2, v5, v2
	v_add_u32_e32 v2, v5, v2
	v_mul_hi_u32 v2, v6, v2
	v_mul_lo_u32 v4, v2, v3
	v_sub_u32_e32 v4, v6, v4
	v_add_u32_e32 v5, 1, v2
	v_cmp_ge_u32_e32 vcc, v4, v3
	s_nop 1
	v_cndmask_b32_e32 v2, v2, v5, vcc
	v_sub_u32_e32 v5, v4, v3
	v_cndmask_b32_e32 v4, v4, v5, vcc
	v_add_u32_e32 v5, 1, v2
	v_cmp_ge_u32_e32 vcc, v4, v3
	v_add_u32_e32 v4, 1, v6
	s_nop 0
	v_cndmask_b32_e32 v2, v2, v5, vcc
	v_mul_lo_u32 v5, v3, v2
	v_add_u32_e32 v3, v5, v3
	v_cmp_ne_u32_e32 vcc, v4, v3
	s_and_saveexec_b64 s[4:5], vcc
	s_xor_b64 s[4:5], exec, s[4:5]
	s_cbranch_execz .LBB0_348
	s_waitcnt lgkmcnt(0)
	v_mov_b32_e32 v1, 0x3500
	global_load_dword v1, v1, s[86:87] sc1
	s_add_u32 s8, s86, 0x3500
	s_addc_u32 s9, s87, 0
	s_waitcnt vmcnt(0)
	v_cmp_eq_u32_e32 vcc, v1, v2
	s_and_saveexec_b64 s[6:7], vcc
	s_cbranch_execz .LBB0_347
	s_mov_b32 s22, 1
	s_mov_b64 s[10:11], 0
	v_mov_b32_e32 v1, 0
	s_branch .LBB0_338

.LBB0_365:
	s_or_b64 exec, exec, s[4:5]
	s_mov_b64 s[4:5], exec
	v_mbcnt_lo_u32_b32 v1, s4, 0
	v_mbcnt_hi_u32_b32 v1, s5, v1
	v_cmp_eq_u32_e32 vcc, 0, v1
	s_waitcnt vmcnt(0)
	buffer_inv sc1
	s_and_saveexec_b64 s[6:7], vcc
	s_cbranch_execz .LBB0_367
	s_bcnt1_i32_b64 s4, s[4:5]
	v_mov_b32_e32 v1, 0x2000
	v_mov_b32_e32 v2, s4
.LBB0_367:
	s_or_b64 exec, exec, s[6:7]
	s_waitcnt vmcnt(0)

.LBB0_1188:
	s_or_b64 exec, exec, s[6:7]
	v_cvt_f32_u32_e32 v5, v3
	s_waitcnt vmcnt(0)
	v_readfirstlane_b32 s4, v4
	v_sub_u32_e32 v4, 0, v3
	v_rcp_iflag_f32_e32 v5, v5
	v_add_u32_e32 v6, s4, v2
	v_mul_f32_e32 v5, 0x4f7ffffe, v5
	v_cvt_u32_f32_e32 v5, v5
	v_mul_lo_u32 v2, v4, v5
	v_mul_hi_u32 v2, v5, v2
	v_add_u32_e32 v2, v5, v2
	v_mul_hi_u32 v2, v6, v2
	v_mul_lo_u32 v4, v2, v3
	v_sub_u32_e32 v4, v6, v4
	v_add_u32_e32 v5, 1, v2
	v_cmp_ge_u32_e32 vcc, v4, v3
	s_nop 1
	v_cndmask_b32_e32 v2, v2, v5, vcc
	v_sub_u32_e32 v5, v4, v3
	v_cndmask_b32_e32 v4, v4, v5, vcc
	v_add_u32_e32 v5, 1, v2
	v_cmp_ge_u32_e32 vcc, v4, v3
	v_add_u32_e32 v4, 1, v6
	s_nop 0
	v_cndmask_b32_e32 v2, v2, v5, vcc
	v_mul_lo_u32 v5, v3, v2
	v_add_u32_e32 v3, v5, v3
	v_cmp_ne_u32_e32 vcc, v4, v3
	s_and_saveexec_b64 s[4:5], vcc
	s_xor_b64 s[4:5], exec, s[4:5]
	s_cbranch_execz .LBB0_1202
	s_waitcnt lgkmcnt(0)
	v_mov_b32_e32 v1, 0x3500
	global_load_dword v1, v1, s[86:87] sc1
	s_add_u32 s8, s86, 0x3500
	s_addc_u32 s9, s87, 0
	s_waitcnt vmcnt(0)
	v_cmp_eq_u32_e32 vcc, v1, v2
	s_and_saveexec_b64 s[6:7], vcc
	s_cbranch_execz .LBB0_1201
	s_mov_b32 s20, 1
	s_mov_b64 s[10:11], 0
	v_mov_b32_e32 v1, 0
	s_branch .LBB0_1192

.LBB0_1219:
	s_or_b64 exec, exec, s[4:5]
	s_mov_b64 s[4:5], exec
	v_mbcnt_lo_u32_b32 v1, s4, 0
	v_mbcnt_hi_u32_b32 v1, s5, v1
	v_cmp_eq_u32_e32 vcc, 0, v1
	s_waitcnt vmcnt(0)
	buffer_inv sc1
	s_and_saveexec_b64 s[6:7], vcc
	s_cbranch_execz .LBB0_1221
	s_bcnt1_i32_b64 s4, s[4:5]
	v_mov_b32_e32 v1, 0x2000
	v_mov_b32_e32 v2, s4
.LBB0_1221:
	s_or_b64 exec, exec, s[6:7]
	s_waitcnt vmcnt(0)

.LBB0_1536:
	s_or_b64 exec, exec, s[4:5]
	s_mov_b64 s[4:5], exec
	v_mbcnt_lo_u32_b32 v1, s4, 0
	v_mbcnt_hi_u32_b32 v1, s5, v1
	v_cmp_eq_u32_e32 vcc, 0, v1
	s_waitcnt vmcnt(0)
	buffer_inv sc1
	s_and_saveexec_b64 s[6:7], vcc
	s_cbranch_execz .LBB0_1538
	s_bcnt1_i32_b64 s4, s[4:5]
	v_mov_b32_e32 v1, 0x2000
	v_mov_b32_e32 v2, s4
.LBB0_1538:
	s_or_b64 exec, exec, s[6:7]
	s_waitcnt vmcnt(0)

.LBB0_1858:
	s_or_b64 exec, exec, s[6:7]
	v_cvt_f32_u32_e32 v6, v4
	s_waitcnt vmcnt(0)
	v_readfirstlane_b32 s4, v5
	v_sub_u32_e32 v5, 0, v4
	v_rcp_iflag_f32_e32 v6, v6
	v_add_u32_e32 v7, s4, v3
	v_mul_f32_e32 v6, 0x4f7ffffe, v6
	v_cvt_u32_f32_e32 v6, v6
	v_mul_lo_u32 v3, v5, v6
	v_mul_hi_u32 v3, v6, v3
	v_add_u32_e32 v3, v6, v3
	v_mul_hi_u32 v3, v7, v3
	v_mul_lo_u32 v5, v3, v4
	v_sub_u32_e32 v5, v7, v5
	v_add_u32_e32 v6, 1, v3
	v_cmp_ge_u32_e32 vcc, v5, v4
	s_nop 1
	v_cndmask_b32_e32 v3, v3, v6, vcc
	v_sub_u32_e32 v6, v5, v4
	v_cndmask_b32_e32 v5, v5, v6, vcc
	v_add_u32_e32 v6, 1, v3
	v_cmp_ge_u32_e32 vcc, v5, v4
	v_add_u32_e32 v5, 1, v7
	s_nop 0
	v_cndmask_b32_e32 v3, v3, v6, vcc
	v_mul_lo_u32 v6, v4, v3
	v_add_u32_e32 v4, v6, v4
	v_cmp_ne_u32_e32 vcc, v5, v4
	s_and_saveexec_b64 s[4:5], vcc
	s_xor_b64 s[4:5], exec, s[4:5]
	s_cbranch_execz .LBB0_1872
	s_waitcnt lgkmcnt(0)
	v_mov_b32_e32 v2, 0x3500
	global_load_dword v2, v2, s[86:87] sc1
	s_add_u32 s8, s86, 0x3500
	s_addc_u32 s9, s87, 0
	s_waitcnt vmcnt(0)
	v_cmp_eq_u32_e32 vcc, v2, v3
	s_and_saveexec_b64 s[6:7], vcc
	s_cbranch_execz .LBB0_1871
	s_mov_b32 s20, 1
	s_mov_b64 s[10:11], 0
	v_mov_b32_e32 v2, 0
	s_branch .LBB0_1862

.LBB0_1889:
	s_or_b64 exec, exec, s[4:5]
	s_mov_b64 s[4:5], exec
	v_mbcnt_lo_u32_b32 v2, s4, 0
	v_mbcnt_hi_u32_b32 v2, s5, v2
	v_cmp_eq_u32_e32 vcc, 0, v2
	s_waitcnt vmcnt(0)
	buffer_inv sc1
	s_and_saveexec_b64 s[6:7], vcc
	s_cbranch_execz .LBB0_1891
	s_bcnt1_i32_b64 s4, s[4:5]
	v_mov_b32_e32 v2, 0x2000
	v_mov_b32_e32 v3, s4
.LBB0_1891:
	s_or_b64 exec, exec, s[6:7]
	s_waitcnt vmcnt(0)

.LBB0_1944:
	s_or_b64 exec, exec, s[4:5]
	s_mov_b64 s[4:5], exec
	v_mbcnt_lo_u32_b32 v2, s4, 0
	v_mbcnt_hi_u32_b32 v2, s5, v2
	v_cmp_eq_u32_e32 vcc, 0, v2
	s_waitcnt vmcnt(0)
	buffer_inv sc1
	s_and_saveexec_b64 s[6:7], vcc
	s_cbranch_execz .LBB0_1946
	s_bcnt1_i32_b64 s4, s[4:5]
	v_mov_b32_e32 v2, 0x2000
	v_mov_b32_e32 v3, s4
.LBB0_1946:
	s_or_b64 exec, exec, s[6:7]
	s_waitcnt vmcnt(0)

.LBB0_2017:
	s_or_b64 exec, exec, s[8:9]
	v_cvt_f32_u32_e32 v6, v4
	s_waitcnt vmcnt(0)
	v_readfirstlane_b32 s6, v5
	v_sub_u32_e32 v5, 0, v4
	v_rcp_iflag_f32_e32 v6, v6
	v_add_u32_e32 v7, s6, v3
	v_mul_f32_e32 v6, 0x4f7ffffe, v6
	v_cvt_u32_f32_e32 v6, v6
	v_mul_lo_u32 v3, v5, v6
	v_mul_hi_u32 v3, v6, v3
	v_add_u32_e32 v3, v6, v3
	v_mul_hi_u32 v3, v7, v3
	v_mul_lo_u32 v5, v3, v4
	v_sub_u32_e32 v5, v7, v5
	v_add_u32_e32 v6, 1, v3
	v_cmp_ge_u32_e32 vcc, v5, v4
	s_nop 1
	v_cndmask_b32_e32 v3, v3, v6, vcc
	v_sub_u32_e32 v6, v5, v4
	v_cndmask_b32_e32 v5, v5, v6, vcc
	v_add_u32_e32 v6, 1, v3
	v_cmp_ge_u32_e32 vcc, v5, v4
	v_add_u32_e32 v5, 1, v7
	s_nop 0
	v_cndmask_b32_e32 v3, v3, v6, vcc
	v_mul_lo_u32 v6, v4, v3
	v_add_u32_e32 v4, v6, v4
	v_cmp_ne_u32_e32 vcc, v5, v4
	s_and_saveexec_b64 s[6:7], vcc
	s_xor_b64 s[6:7], exec, s[6:7]
	s_cbranch_execz .LBB0_2031
	s_waitcnt lgkmcnt(0)
	v_mov_b32_e32 v2, 0x3500
	global_load_dword v2, v2, s[86:87] sc1
	s_add_u32 s10, s86, 0x3500
	s_addc_u32 s11, s87, 0
	s_waitcnt vmcnt(0)
	v_cmp_eq_u32_e32 vcc, v2, v3
	s_and_saveexec_b64 s[8:9], vcc
	s_cbranch_execz .LBB0_2030
	s_mov_b32 s22, 1
	s_mov_b64 s[12:13], 0
	v_mov_b32_e32 v2, 0
	s_branch .LBB0_2021

.LBB0_2048:
	s_or_b64 exec, exec, s[6:7]
	s_mov_b64 s[6:7], exec
	v_mbcnt_lo_u32_b32 v2, s6, 0
	v_mbcnt_hi_u32_b32 v2, s7, v2
	v_cmp_eq_u32_e32 vcc, 0, v2
	s_waitcnt vmcnt(0)
	buffer_inv sc1
	s_and_saveexec_b64 s[8:9], vcc
	s_cbranch_execz .LBB0_2050
	s_bcnt1_i32_b64 s6, s[6:7]
	v_mov_b32_e32 v2, 0x2000
	v_mov_b32_e32 v3, s6
.LBB0_2050:
	s_or_b64 exec, exec, s[8:9]
	s_waitcnt vmcnt(0)

.LBB0_2124:
	s_or_b64 exec, exec, s[6:7]
	s_mov_b64 s[6:7], exec
	v_mbcnt_lo_u32_b32 v2, s6, 0
	v_mbcnt_hi_u32_b32 v2, s7, v2
	v_cmp_eq_u32_e32 vcc, 0, v2
	s_waitcnt vmcnt(0)
	buffer_inv sc1
	s_and_saveexec_b64 s[8:9], vcc
	s_cbranch_execz .LBB0_2126
	s_bcnt1_i32_b64 s6, s[6:7]
	v_mov_b32_e32 v2, 0x2000
	v_mov_b32_e32 v3, s6
.LBB0_2126:
	s_or_b64 exec, exec, s[8:9]
	s_waitcnt vmcnt(0)

.LBB0_2242:
	s_or_b64 exec, exec, s[6:7]
	v_cvt_f32_u32_e32 v6, v4
	s_waitcnt vmcnt(0)
	v_readfirstlane_b32 s4, v5
	v_sub_u32_e32 v5, 0, v4
	v_rcp_iflag_f32_e32 v6, v6
	v_add_u32_e32 v7, s4, v3
	v_mul_f32_e32 v6, 0x4f7ffffe, v6
	v_cvt_u32_f32_e32 v6, v6
	v_mul_lo_u32 v3, v5, v6
	v_mul_hi_u32 v3, v6, v3
	v_add_u32_e32 v3, v6, v3
	v_mul_hi_u32 v3, v7, v3
	v_mul_lo_u32 v5, v3, v4
	v_sub_u32_e32 v5, v7, v5
	v_add_u32_e32 v6, 1, v3
	v_cmp_ge_u32_e32 vcc, v5, v4
	s_nop 1
	v_cndmask_b32_e32 v3, v3, v6, vcc
	v_sub_u32_e32 v6, v5, v4
	v_cndmask_b32_e32 v5, v5, v6, vcc
	v_add_u32_e32 v6, 1, v3
	v_cmp_ge_u32_e32 vcc, v5, v4
	v_add_u32_e32 v5, 1, v7
	s_nop 0
	v_cndmask_b32_e32 v3, v3, v6, vcc
	v_mul_lo_u32 v6, v4, v3
	v_add_u32_e32 v4, v6, v4
	v_cmp_ne_u32_e32 vcc, v5, v4
	s_and_saveexec_b64 s[4:5], vcc
	s_xor_b64 s[4:5], exec, s[4:5]
	s_cbranch_execz .LBB0_2256
	s_waitcnt lgkmcnt(0)
	v_mov_b32_e32 v2, 0x3500
	global_load_dword v2, v2, s[86:87] sc1
	s_add_u32 s10, s86, 0x3500
	s_addc_u32 s11, s87, 0
	s_waitcnt vmcnt(0)
	v_cmp_eq_u32_e32 vcc, v2, v3
	s_and_saveexec_b64 s[6:7], vcc
	s_cbranch_execz .LBB0_2255
	s_mov_b32 s22, 1
	s_mov_b64 s[12:13], 0
	v_mov_b32_e32 v2, 0
	s_branch .LBB0_2246

.LBB0_2273:
	s_or_b64 exec, exec, s[4:5]
	s_mov_b64 s[4:5], exec
	v_mbcnt_lo_u32_b32 v2, s4, 0
	v_mbcnt_hi_u32_b32 v2, s5, v2
	v_cmp_eq_u32_e32 vcc, 0, v2
	s_waitcnt vmcnt(0)
	buffer_inv sc1
	s_and_saveexec_b64 s[6:7], vcc
	s_cbranch_execz .LBB0_2275
	s_bcnt1_i32_b64 s4, s[4:5]
	v_mov_b32_e32 v2, 0x2000
	v_mov_b32_e32 v3, s4
.LBB0_2275:
	s_or_b64 exec, exec, s[6:7]
	s_waitcnt vmcnt(0)
